# attention: next chunk's K/V loaded straight into the MFMA operand registers (K after QK, V after PV, counted vmcnt), no per-chunk register rotation
# speedup vs baseline: 1.0057x; 1.0057x over previous
.LBB0_595:
	v_and_b32_e32 v164, 3, v125
	v_and_b32_e32 v165, 0x700, v125
	v_lshl_or_b32 v165, v164, 6, v165
	v_bfe_u32 v166, v125, 2, 6
	v_or_b32_e32 v165, v165, v166
	v_and_b32_e32 v167, 0xfe0, v125
	v_lshl_or_b32 v167, v164, 3, v167
	v_bfe_u32 v166, v125, 2, 3
	v_or_b32_e32 v167, v167, v166
	v_mov_b32_e32 v166, 0x800
	v_cmp_lt_i32_e32 vcc, v125, v166
	s_nop 1
	v_cndmask_b32_e32 v163, v167, v165, vcc
	s_movk_i32 s0, 0x7ff
	v_cmp_lt_i32_e64 s[70:71], s0, v125
	s_movk_i32 s0, 0x800
	v_cmp_gt_i32_e32 vcc, s0, v125
	v_lshlrev_b32_e32 v4, 5, v163
	v_lshrrev_b32_e32 v3, 2, v163
	s_and_saveexec_b64 s[0:1], vcc
	s_xor_b64 s[0:1], exec, s[0:1]
	s_cbranch_execz .LBB0_597
	v_ashrrev_i32_e32 v36, 9, v163
	v_and_b32_e32 v1, 0x7e0, v4
	v_lshlrev_b32_e32 v4, 7, v36
	v_and_or_b32 v4, v3, 64, v4
	v_sub_u32_e32 v3, 0x80, v1
	s_movk_i32 s2, 0x80
	v_ashrrev_i32_e32 v3, 5, v3
	v_cmp_gt_u32_e32 vcc, s2, v1
	v_ashrrev_i32_e32 v5, 31, v4
	v_lshl_or_b32 v2, v36, 11, v1
	v_cndmask_b32_e32 v144, 0, v3, vcc
	v_sub_u32_e32 v3, 0x860, v1
	v_lshrrev_b32_e32 v3, 5, v3
	v_min_u32_e32 v3, 8, v3
	v_lshlrev_b64 v[4:5], 12, v[4:5]
	v_sub_u32_e32 v3, v3, v144
	v_lshrrev_b32_e32 v0, 6, v163
	v_add_u32_e32 v2, 0x1000, v2
	v_lshl_add_u64 v[130:131], s[76:77], 0, v[4:5]
	v_lshl_add_u64 v[132:133], s[84:85], 0, v[4:5]
	v_add_u32_e32 v127, 1, v3
.LBB0_597:
	s_andn2_saveexec_b64 s[0:1], s[0:1]
	s_cbranch_execz .LBB0_599
	v_add_u32_e32 v0, 0xfffff800, v163
	v_lshrrev_b32_e32 v36, 6, v0
	v_and_b32_e32 v3, 8, v3
	v_lshl_or_b32 v168, v36, 4, v3
	v_readlane_b32 s2, v254, 62
	v_and_b32_e32 v1, 0xe0, v4
	v_lshlrev_b64 v[4:5], 12, v[168:169]
	v_readlane_b32 s3, v254, 63
	v_lshrrev_b32_e32 v0, 3, v163
	v_mov_b32_e32 v127, 8
	v_lshl_add_u64 v[130:131], s[2:3], 0, v[4:5]
	v_readlane_b32 s2, v255, 0
	v_readlane_b32 s3, v255, 1
	v_lshl_or_b32 v2, v36, 8, v1
	v_mov_b32_e32 v144, 0
	v_lshl_add_u64 v[132:133], s[2:3], 0, v[4:5]
.LBB0_599:
	s_or_b64 exec, exec, s[0:1]
	v_readlane_b32 s0, v254, 44
	v_add_u32_e32 v1, 0xffffff80, v1
	v_add_u32_e32 v134, v2, v139
	v_mov_b32_e32 v4, s0
	ds_read_b64 v[4:5], v4
	v_ashrrev_i32_e32 v1, 5, v1
	v_ashrrev_i32_e32 v135, 31, v134
	v_cndmask_b32_e64 v1, v1, 0, s[70:71]
	v_and_b32_e32 v16, 7, v0
	v_lshlrev_b64 v[2:3], 10, v[134:135]
	v_add_u32_e32 v136, v1, v144
	v_lshl_add_u64 v[2:3], s[88:89], 0, v[2:3]
	v_lshlrev_b32_e32 v168, 7, v16
	v_ashrrev_i32_e32 v137, 31, v136
	v_lshl_add_u64 v[2:3], v[2:3], 0, v[168:169]
	v_mov_b32_e32 v129, v169
	s_waitcnt lgkmcnt(0)
	v_readfirstlane_b32 s1, v5
	v_readfirstlane_b32 s0, v4
	v_lshlrev_b64 v[4:5], 12, v[136:137]
	v_lshl_add_u64 v[2:3], v[2:3], 0, v[128:129]
	v_lshlrev_b32_e32 v1, 2, v16
	v_lshl_add_u64 v[6:7], v[132:133], 0, v[4:5]
	v_lshlrev_b32_e32 v168, 1, v124
	v_lshl_add_u64 v[4:5], v[130:131], 0, v[4:5]
	global_load_dwordx4 v[48:51], v[2:3], off
	global_load_dwordx4 v[52:55], v[2:3], off offset:32
	global_load_dword v38, v1, s[0:1]
	v_lshl_add_u64 v[4:5], v[4:5], 0, v[168:169]
	v_lshl_add_u64 v[6:7], v[6:7], 0, v[168:169]
	global_load_dwordx4 v[152:155], v[4:5], off offset:3072
	global_load_dwordx4 v[116:119], v[4:5], off offset:2048
	global_load_dwordx4 v[120:123], v[4:5], off offset:1024
	global_load_dwordx4 v[148:151], v[4:5], off
	global_load_dwordx4 v[64:67], v[6:7], off offset:3072
	global_load_dwordx4 v[72:75], v[6:7], off offset:2048
	global_load_dwordx4 v[68:71], v[6:7], off offset:1024
	global_load_dwordx4 v[76:79], v[6:7], off
	global_load_dwordx4 v[56:59], v[2:3], off offset:64
	global_load_dwordx4 v[60:63], v[2:3], off offset:96
	v_lshlrev_b32_e32 v17, 2, v0
	v_and_b32_e32 v37, 16, v17
	v_lshl_or_b32 v36, v36, 5, v37
	v_add_u32_e32 v18, 16, v127
	v_mov_b32_e32 v14, v169
	v_mov_b32_e32 v15, v169
	v_ashrrev_i32_e32 v37, 31, v36
	v_mov_b32_e32 v0, v169
	v_mov_b32_e32 v1, v169
	v_mov_b32_e32 v2, v169
	v_mov_b32_e32 v3, v169
	v_mov_b32_e32 v4, v169
	v_mov_b32_e32 v5, v169
	v_mov_b32_e32 v6, v169
	v_mov_b32_e32 v7, v169
	v_mov_b32_e32 v8, v169
	v_mov_b32_e32 v9, v169
	v_mov_b32_e32 v10, v169
	v_mov_b32_e32 v11, v169
	v_mov_b32_e32 v12, v169
	v_mov_b32_e32 v13, v169
	v_lshlrev_b32_e32 v138, 6, v16
	v_cndmask_b32_e64 v145, v18, v127, s[70:71]
	v_mov_b64_e32 v[30:31], v[14:15]
	v_lshlrev_b64 v[36:37], 12, v[36:37]
	s_mov_b32 s92, 1
	v_sub_u32_e32 v129, 0, v127
	v_mov_b32_e32 v137, 1.0
	s_mov_b64 s[2:3], 0
	v_mov_b64_e32 v[28:29], v[12:13]
	v_mov_b64_e32 v[26:27], v[10:11]
	v_mov_b64_e32 v[24:25], v[8:9]
	v_mov_b64_e32 v[22:23], v[6:7]
	v_mov_b64_e32 v[20:21], v[4:5]
	v_mov_b64_e32 v[18:19], v[2:3]
	v_mov_b64_e32 v[16:17], v[0:1]
	v_sub_u32_e32 v146, 0, v145
	v_lshl_add_u64 v[140:141], s[82:83], 0, v[36:37]
	v_lshl_add_u64 v[142:143], s[80:81], 0, v[36:37]
	s_waitcnt vmcnt(0)
	v_mul_f32_e32 v147, 0x3fb8aa3b, v38
	s_branch .LBB0_601
.LBB0_600:
	v_fma_f32 v32, v32, s33, -v147
	v_exp_f32_e32 v32, v32
	v_fma_f32 v33, v33, s33, -v147
	v_exp_f32_e32 v33, v33
	v_fma_f32 v34, v34, s33, -v147
	v_exp_f32_e32 v34, v34
	v_fma_f32 v35, v35, s33, -v147
	v_exp_f32_e32 v35, v35
	v_fma_f32 v36, v36, s33, -v147
	v_add_f32_e32 v112, 0, v32
	v_exp_f32_e32 v36, v36
	v_fma_f32 v37, v37, s33, -v147
	v_add_f32_e32 v112, v33, v112
	v_exp_f32_e32 v37, v37
	v_fma_f32 v38, v38, s33, -v147
	v_add_f32_e32 v112, v34, v112
	v_exp_f32_e32 v38, v38
	v_fma_f32 v39, v39, s33, -v147
	v_add_f32_e32 v112, v35, v112
	v_exp_f32_e32 v39, v39
	v_fma_f32 v40, v40, s33, -v147
	v_add_f32_e32 v112, v36, v112
	v_exp_f32_e32 v40, v40
	v_fma_f32 v41, v41, s33, -v147
	v_add_f32_e32 v112, v37, v112
	v_exp_f32_e32 v41, v41
	v_fma_f32 v42, v42, s33, -v147
	v_add_f32_e32 v112, v38, v112
	v_exp_f32_e32 v42, v42
	v_fma_f32 v43, v43, s33, -v147
	v_add_f32_e32 v112, v39, v112
	v_exp_f32_e32 v43, v43
	v_fma_f32 v44, v44, s33, -v147
	v_add_f32_e32 v112, v40, v112
	v_exp_f32_e32 v44, v44
	v_fma_f32 v45, v45, s33, -v147
	v_add_f32_e32 v112, v41, v112
	v_exp_f32_e32 v45, v45
	v_fma_f32 v46, v46, s33, -v147
	v_add_f32_e32 v112, v42, v112
	v_exp_f32_e32 v46, v46
	v_fma_f32 v47, v47, s33, -v147
	v_add_f32_e32 v112, v43, v112
	v_exp_f32_e32 v47, v47
	v_add_f32_e32 v112, v44, v112
	v_add_f32_e32 v112, v45, v112
	v_add_f32_e32 v112, v46, v112
	v_add_f32_e32 v112, v47, v112
	v_mov_b32_e32 v113, v112
	s_nop 1
	v_permlane32_swap_b32_e32 v112, v113
	v_add_f32_e32 v112, v112, v113
	v_cvt_pk_bf16_f32 v32, v32, v33
	v_cvt_pk_bf16_f32 v33, v34, v35
	v_cvt_pk_bf16_f32 v34, v36, v37
	v_cvt_pk_bf16_f32 v35, v38, v39
	s_waitcnt vmcnt(4)
	s_setprio 1
	s_nop 0
	v_mfma_f32_32x32x16_bf16 v[16:31], v[76:79], v[32:35], v[16:31]
	v_mfma_f32_32x32x16_bf16 v[0:15], v[72:75], v[32:35], v[0:15]
	s_setprio 0
	v_cvt_pk_bf16_f32 v32, v40, v41
	v_cvt_pk_bf16_f32 v33, v42, v43
	v_cvt_pk_bf16_f32 v34, v44, v45
	v_cvt_pk_bf16_f32 v35, v46, v47
	s_setprio 1
	s_nop 0
	v_mfma_f32_32x32x16_bf16 v[16:31], v[68:71], v[32:35], v[16:31]
	v_mfma_f32_32x32x16_bf16 v[0:15], v[64:67], v[32:35], v[0:15]
	s_setprio 0
	s_add_i32 s92, s92, 1
	v_add_u32_e32 v32, s92, v146
	v_add_f32_e32 v137, v137, v112
	v_cmp_eq_u32_e32 vcc, 1, v32
	s_or_b64 s[2:3], vcc, s[2:3]
	global_load_dwordx4 v[76:79], v[158:159], off
	global_load_dwordx4 v[68:71], v[158:159], off offset:1024
	global_load_dwordx4 v[72:75], v[158:159], off offset:2048
	global_load_dwordx4 v[64:67], v[158:159], off offset:3072
	s_andn2_b64 exec, exec, s[2:3]
	s_cbranch_execz .LBB0_594
.LBB0_601:
	v_add_u32_e32 v38, s92, v136
	v_add_u32_e32 v36, s92, v129
	v_ashrrev_i32_e32 v37, 31, v38
	v_cmp_lt_i32_e32 vcc, s92, v127
	s_nop 1
	v_cndmask_b32_e32 v37, 0, v37, vcc
	v_cndmask_b32_e32 v36, v36, v38, vcc
	v_cndmask_b32_e32 v39, v141, v131, vcc
	v_cndmask_b32_e32 v38, v140, v130, vcc
	v_lshlrev_b64 v[36:37], 12, v[36:37]
	v_cndmask_b32_e32 v41, v143, v133, vcc
	v_cndmask_b32_e32 v40, v142, v132, vcc
	v_lshl_add_u64 v[38:39], v[38:39], 0, v[36:37]
	v_lshl_add_u64 v[36:37], v[40:41], 0, v[36:37]
	v_lshl_add_u64 v[156:157], v[38:39], 0, v[168:169]
	v_lshl_add_u64 v[158:159], v[36:37], 0, v[168:169]
.LBB0_603:
	s_add_i32 s0, s92, -1
	v_cmp_ge_i32_e32 vcc, s0, v127
	v_add_u32_e32 v36, s92, v144
	s_or_b64 s[94:95], s[70:71], vcc
	v_cmp_ne_u32_e32 vcc, 1, v36
	v_cmp_ne_u32_e64 s[0:1], 9, v36
	s_setprio 1
	s_waitcnt vmcnt(4)
	v_mfma_f32_32x32x16_bf16 v[32:47], v[148:151], v[48:51], 0
	v_mfma_f32_32x32x16_bf16 v[32:47], v[120:123], v[52:55], v[32:47]
	v_mfma_f32_32x32x16_bf16 v[32:47], v[116:119], v[56:59], v[32:47]
	v_mfma_f32_32x32x16_bf16 v[32:47], v[152:155], v[60:63], v[32:47]
	s_setprio 0
	global_load_dwordx4 v[148:151], v[156:157], off
	global_load_dwordx4 v[120:123], v[156:157], off offset:1024
	global_load_dwordx4 v[116:119], v[156:157], off offset:2048
	global_load_dwordx4 v[152:155], v[156:157], off offset:3072
	s_and_b64 s[0:1], vcc, s[0:1]
	s_nor_b64 s[0:1], s[94:95], s[0:1]
	s_and_saveexec_b64 s[94:95], s[0:1]
	s_cbranch_execz .LBB0_605
	v_cndmask_b32_e64 v112, 0, 1, s[6:7]
	v_cndmask_b32_e64 v113, 0, 1, s[4:5]
	v_cndmask_b32_e32 v112, v113, v112, vcc
	v_and_b32_e32 v112, 1, v112
	v_cmp_eq_u32_e64 s[0:1], 1, v112
	v_cndmask_b32_e64 v112, 0, 1, s[10:11]
	v_cndmask_b32_e64 v113, 0, 1, s[8:9]
	v_cndmask_b32_e32 v112, v113, v112, vcc
	v_and_b32_e32 v112, 1, v112
	v_cndmask_b32_e64 v32, v233, v32, s[0:1]
	v_cmp_eq_u32_e64 s[0:1], 1, v112
	v_cndmask_b32_e64 v112, 0, 1, s[14:15]
	v_cndmask_b32_e64 v113, 0, 1, s[12:13]
	v_cndmask_b32_e32 v112, v113, v112, vcc
	v_and_b32_e32 v112, 1, v112
	v_cndmask_b32_e64 v33, v233, v33, s[0:1]
	v_cmp_eq_u32_e64 s[0:1], 1, v112
	v_cndmask_b32_e64 v112, 0, 1, s[18:19]
	v_cndmask_b32_e64 v113, 0, 1, s[16:17]
	v_cndmask_b32_e32 v112, v113, v112, vcc
	v_and_b32_e32 v112, 1, v112
	v_cndmask_b32_e64 v34, v233, v34, s[0:1]
	v_cmp_eq_u32_e64 s[0:1], 1, v112
	v_cndmask_b32_e64 v112, 0, 1, s[22:23]
	v_cndmask_b32_e64 v113, 0, 1, s[20:21]
	v_cndmask_b32_e32 v112, v113, v112, vcc
	v_and_b32_e32 v112, 1, v112
	v_cndmask_b32_e64 v35, v233, v35, s[0:1]
	v_cmp_eq_u32_e64 s[0:1], 1, v112
	v_cndmask_b32_e64 v112, 0, 1, s[26:27]
	v_cndmask_b32_e64 v113, 0, 1, s[24:25]
	v_cndmask_b32_e32 v112, v113, v112, vcc
	v_and_b32_e32 v112, 1, v112
	v_cndmask_b32_e64 v36, v233, v36, s[0:1]
	v_cmp_eq_u32_e64 s[0:1], 1, v112
	v_cndmask_b32_e64 v112, 0, 1, s[30:31]
	v_cndmask_b32_e64 v113, 0, 1, s[28:29]
	v_cndmask_b32_e32 v112, v113, v112, vcc
	v_and_b32_e32 v112, 1, v112
	v_cndmask_b32_e64 v37, v233, v37, s[0:1]
	v_cmp_eq_u32_e64 s[0:1], 1, v112
	v_cndmask_b32_e64 v112, 0, 1, s[36:37]
	v_cndmask_b32_e64 v113, 0, 1, s[34:35]
	v_cndmask_b32_e32 v112, v113, v112, vcc
	v_and_b32_e32 v112, 1, v112
	v_cndmask_b32_e64 v38, v233, v38, s[0:1]
	v_cmp_eq_u32_e64 s[0:1], 1, v112
	v_cndmask_b32_e64 v112, 0, 1, s[40:41]
	v_cndmask_b32_e64 v113, 0, 1, s[38:39]
	v_cndmask_b32_e32 v112, v113, v112, vcc
	v_and_b32_e32 v112, 1, v112
	v_cndmask_b32_e64 v39, v233, v39, s[0:1]
	v_cmp_eq_u32_e64 s[0:1], 1, v112
	v_cndmask_b32_e64 v112, 0, 1, s[44:45]
	v_cndmask_b32_e64 v113, 0, 1, s[42:43]
	v_cndmask_b32_e32 v112, v113, v112, vcc
	v_and_b32_e32 v112, 1, v112
	v_cndmask_b32_e64 v40, v233, v40, s[0:1]
	v_cmp_eq_u32_e64 s[0:1], 1, v112
	v_cndmask_b32_e64 v112, 0, 1, s[48:49]
	v_cndmask_b32_e64 v113, 0, 1, s[46:47]
	v_cndmask_b32_e32 v112, v113, v112, vcc
	v_and_b32_e32 v112, 1, v112
	v_cndmask_b32_e64 v41, v233, v41, s[0:1]
	v_cmp_eq_u32_e64 s[0:1], 1, v112
	v_cndmask_b32_e64 v112, 0, 1, s[52:53]
	v_cndmask_b32_e64 v113, 0, 1, s[50:51]
	v_cndmask_b32_e32 v112, v113, v112, vcc
	v_and_b32_e32 v112, 1, v112
	v_cndmask_b32_e64 v42, v233, v42, s[0:1]
	v_cmp_eq_u32_e64 s[0:1], 1, v112
	v_cndmask_b32_e64 v112, 0, 1, s[56:57]
	v_cndmask_b32_e64 v113, 0, 1, s[54:55]
	v_cndmask_b32_e32 v112, v113, v112, vcc
	v_and_b32_e32 v112, 1, v112
	v_cndmask_b32_e64 v43, v233, v43, s[0:1]
	v_cmp_eq_u32_e64 s[0:1], 1, v112
	v_cndmask_b32_e64 v112, 0, 1, s[60:61]
	v_cndmask_b32_e64 v113, 0, 1, s[58:59]
	v_cndmask_b32_e32 v112, v113, v112, vcc
	v_and_b32_e32 v112, 1, v112
	v_cndmask_b32_e64 v44, v233, v44, s[0:1]
	v_cmp_eq_u32_e64 s[0:1], 1, v112
	v_cndmask_b32_e64 v112, 0, 1, s[64:65]
	v_cndmask_b32_e64 v113, 0, 1, s[62:63]
	v_cndmask_b32_e32 v112, v113, v112, vcc
	v_and_b32_e32 v112, 1, v112
	v_cndmask_b32_e64 v45, v233, v45, s[0:1]
	v_cmp_eq_u32_e64 s[0:1], 1, v112
	v_cndmask_b32_e64 v112, 0, 1, s[68:69]
	v_cndmask_b32_e64 v113, 0, 1, s[66:67]
	v_cndmask_b32_e32 v112, v113, v112, vcc
	v_and_b32_e32 v112, 1, v112
	v_cmp_eq_u32_e32 vcc, 1, v112
	v_cndmask_b32_e64 v46, v233, v46, s[0:1]
	s_nop 0
	v_cndmask_b32_e32 v47, v233, v47, vcc
